# W_pg-in-P2 version plus dropped barrier before the weight-copy tail
# speedup vs baseline: 1.0003x; 1.0003x over previous
; #define PG8_WAIT_V(n) asm volatile("s_waitcnt vmcnt(" #n ")" ::: "memory")
; #define PG8_BAR __builtin_amdgcn_s_barrier()
;     ...
;     PG8_WAIT_V(0);
;     if constexpr (!ALIGN_EPI) { if (wr == 0) PG8_BAR; }
;     PG8_BAR;
; __global__ void __launch_bounds__(NWAVES * 64, 2) fwd_kernel(Args args) {
;     ...
;         if (G == 256 && bx >= 128) {
;             int tl_ = threadIdx.x; asm volatile("" : "+v"(tl_));
;             convert_weights(args, WI_P1 + WI_OUT, WI_ALL, (bx - 128) * NWAVES + wave, 128 * NWAVES, tl_ & 63);
;         }
.LBB0_404:
	v_readlane_b32 s76, v254, 38
	v_readlane_b32 s79, v254, 41
	s_mov_b64 s[72:73], s[84:85]
	s_mov_b32 s79, s88
	s_mov_b32 s84, s89
	v_readlane_b32 s92, v254, 36
	v_readlane_b32 s94, v254, 34
	v_readlane_b32 s96, v254, 32
	v_readlane_b32 s70, v254, 27
	v_readlane_b32 s88, v254, 30
	v_readlane_b32 s77, v254, 39
	v_readlane_b32 s78, v254, 40
	v_readlane_b32 s93, v254, 37
	v_readlane_b32 s95, v254, 35
	v_readlane_b32 s97, v254, 33
	v_readlane_b32 s71, v254, 28
	v_readlane_b32 s89, v254, 31
	v_readlane_b32 s85, v254, 29
.LBB0_405:
	s_cmpk_lt_i32 s10, 0x80
	s_cselect_b64 s[0:1], -1, 0
	s_xor_b64 s[2:3], s[88:89], -1
	s_or_b64 s[0:1], s[0:1], s[2:3]
	s_and_b64 vcc, exec, s[0:1]
	s_cbranch_vccnz .LBB0_453
	s_lshl_b32 s0, s10, 3
	v_readlane_b32 s1, v254, 22
	s_add_i32 s25, s0, s1
	s_addk_i32 s25, 0xfc00
